# code placement: .p2align 6 on the four main GEMM K-loop heads
# baseline (speedup 1.0000x reference)
;     DI bool next(int i, pg8::Unit& o) const { if (i == 0 && has) { o = u; return true; } return false; }
; template <class Epi, class Sched, bool ALIGN_EPI = false, bool SP2 = false>
; __device__ __forceinline__ void gemm_phase(PG8_LAS unsigned char* lds, const Gemm g, const Sched& S, const Epi& E, int wv) {
;     ...
;     for (;;) {
;         const bool has_next = S.next(ui + 1, nxt);
;         const char* nA = has_next ? (const char*)(nxt.sw ? g.A2 : g.A) + (size_t)nxt.pm * tstepA : cA; const char* nB = has_next ? (const char*)(nxt.sw ? g.Bt2 : g.Bt) + (size_t)nxt.pn * tstepB : cB;
;         for (int t = 0; t < nt; t += 2) {
;             const bool last = (t == nt - 2);
;             const char* a1 = cA + (size_t)(t + 1) * kstep;
;             const char* a2 = last ? nA : cA + (size_t)(t + 2) * kstep; const char* b2 = last ? nB : cB + (size_t)(t + 2) * kstep;
;             const char* a3 = a2 + kstep; const char* b3 = b2 + kstep;
;     ...
; #pragma unroll
;         for (int a = 0; a < 2; ++a)
; #pragma unroll
;             for (int b = 0; b < 2; ++b)
; #pragma unroll
;                 for (int m = 0; m < 4; ++m)
; #pragma unroll
;                     for (int n = 0; n < 2; ++n) acc[a][b][m][n] = (f32x4){0.f, 0.f, 0.f, 0.f};
.LBB0_129:
	s_ashr_i32 s25, s24, 31
	s_lshl_b64 s[26:27], s[24:25], 20
	s_cmp_eq_u32 s55, 0
	v_readlane_b32 s23, v254, 60
	s_cselect_b32 s16, s28, s1
	s_cselect_b32 s25, s23, s28
	v_readlane_b32 s23, v254, 61
	s_cselect_b32 s5, s29, s9
	s_cselect_b32 s28, s23, s29
	s_add_u32 s40, s16, s26
	s_addc_u32 s41, s5, s27
	s_and_b64 s[26:27], s[38:39], exec
	s_cselect_b32 s5, s41, s7
	s_cselect_b32 s16, s40, s6
	s_ashr_i32 s23, s22, 31
	s_lshl_b64 s[26:27], s[22:23], 20
	s_add_u32 s42, s25, s26
	s_addc_u32 s43, s28, s27
	s_and_b64 s[26:27], s[38:39], exec
	s_cselect_b32 s23, s43, s3
	s_cselect_b32 s25, s42, s2
	s_add_u32 s35, s2, 0x100
	s_addc_u32 s44, s3, 0
	s_add_u32 s2, s6, 0x80080
	v_mov_b32_e32 v2, 0
	s_addc_u32 s3, s7, 0
	s_mov_b32 s45, -2
	v_mov_b32_e32 v3, v2
	v_mov_b32_e32 v4, v2
	v_mov_b32_e32 v5, v2
	v_mov_b32_e32 v6, v2
	v_mov_b32_e32 v7, v2
	v_mov_b32_e32 v8, v2
	v_mov_b32_e32 v9, v2
	v_mov_b32_e32 v18, v2
	v_mov_b32_e32 v19, v2
	v_mov_b32_e32 v20, v2
	v_mov_b32_e32 v21, v2
	v_mov_b32_e32 v22, v2
	v_mov_b32_e32 v23, v2
	v_mov_b32_e32 v24, v2
	v_mov_b32_e32 v25, v2
	v_mov_b32_e32 v34, v2
	v_mov_b32_e32 v35, v2
	v_mov_b32_e32 v36, v2
	v_mov_b32_e32 v37, v2
	v_mov_b32_e32 v38, v2
	v_mov_b32_e32 v39, v2
	v_mov_b32_e32 v40, v2
	v_mov_b32_e32 v41, v2
	v_mov_b32_e32 v50, v2
	v_mov_b32_e32 v51, v2
	v_mov_b32_e32 v52, v2
	v_mov_b32_e32 v53, v2
	v_mov_b32_e32 v54, v2
	v_mov_b32_e32 v55, v2
	v_mov_b32_e32 v56, v2
	v_mov_b32_e32 v57, v2
	v_mov_b32_e32 v10, v2
	v_mov_b32_e32 v11, v2
	v_mov_b32_e32 v12, v2
	v_mov_b32_e32 v13, v2
	v_mov_b32_e32 v14, v2
	v_mov_b32_e32 v15, v2
	v_mov_b32_e32 v16, v2
	v_mov_b32_e32 v17, v2
	v_mov_b32_e32 v26, v2
	v_mov_b32_e32 v27, v2
	v_mov_b32_e32 v28, v2
	v_mov_b32_e32 v29, v2
	v_mov_b32_e32 v30, v2
	v_mov_b32_e32 v31, v2
	v_mov_b32_e32 v32, v2
	v_mov_b32_e32 v33, v2
	v_mov_b32_e32 v42, v2
	v_mov_b32_e32 v43, v2
	v_mov_b32_e32 v44, v2
	v_mov_b32_e32 v45, v2
	v_mov_b32_e32 v46, v2
	v_mov_b32_e32 v47, v2
	v_mov_b32_e32 v48, v2
	v_mov_b32_e32 v49, v2
	v_mov_b32_e32 v58, v2
	v_mov_b32_e32 v59, v2
	v_mov_b32_e32 v60, v2
	v_mov_b32_e32 v61, v2
	v_mov_b32_e32 v62, v2
	v_mov_b32_e32 v63, v2
	v_mov_b32_e32 v64, v2
	v_mov_b32_e32 v65, v2
	v_mov_b32_e32 v66, v2
	v_mov_b32_e32 v67, v2
	v_mov_b32_e32 v68, v2
	v_mov_b32_e32 v69, v2
	v_mov_b32_e32 v70, v2
	v_mov_b32_e32 v71, v2
	v_mov_b32_e32 v72, v2
	v_mov_b32_e32 v73, v2
	v_mov_b32_e32 v82, v2
	v_mov_b32_e32 v83, v2
	v_mov_b32_e32 v84, v2
	v_mov_b32_e32 v85, v2
	v_mov_b32_e32 v86, v2
	v_mov_b32_e32 v87, v2
	v_mov_b32_e32 v88, v2
	v_mov_b32_e32 v89, v2
	v_mov_b32_e32 v98, v2
	v_mov_b32_e32 v99, v2
	v_mov_b32_e32 v100, v2
	v_mov_b32_e32 v101, v2
	v_mov_b32_e32 v102, v2
	v_mov_b32_e32 v103, v2
	v_mov_b32_e32 v104, v2
	v_mov_b32_e32 v105, v2
	v_mov_b32_e32 v114, v2
	v_mov_b32_e32 v115, v2
	v_mov_b32_e32 v116, v2
	v_mov_b32_e32 v117, v2
	v_mov_b32_e32 v118, v2
	v_mov_b32_e32 v119, v2
	v_mov_b32_e32 v120, v2
	v_mov_b32_e32 v121, v2
	v_mov_b32_e32 v74, v2
	v_mov_b32_e32 v75, v2
	v_mov_b32_e32 v76, v2
	v_mov_b32_e32 v77, v2
	v_mov_b32_e32 v78, v2
	v_mov_b32_e32 v79, v2
	v_mov_b32_e32 v80, v2
	v_mov_b32_e32 v81, v2
	v_mov_b32_e32 v90, v2
	v_mov_b32_e32 v91, v2
	v_mov_b32_e32 v92, v2
	v_mov_b32_e32 v93, v2
	v_mov_b32_e32 v94, v2
	v_mov_b32_e32 v95, v2
	v_mov_b32_e32 v96, v2
	v_mov_b32_e32 v97, v2
	v_mov_b32_e32 v106, v2
	v_mov_b32_e32 v107, v2
	v_mov_b32_e32 v108, v2
	v_mov_b32_e32 v109, v2
	v_mov_b32_e32 v110, v2
	v_mov_b32_e32 v111, v2
	v_mov_b32_e32 v112, v2
	v_mov_b32_e32 v113, v2
	v_mov_b32_e32 v122, v2
	v_mov_b32_e32 v123, v2
	v_mov_b32_e32 v124, v2
	v_mov_b32_e32 v125, v2
	v_mov_b32_e32 v126, v2
	v_mov_b32_e32 v127, v2
	v_mov_b32_e32 v128, v2
	v_mov_b32_e32 v129, v2
	.p2align 6

;     DI bool next(int i, pg8::Unit& o) const { if (i == 0 && has) { o = u; return true; } return false; }
; template <class Epi, class Sched, bool ALIGN_EPI = false, bool SP2 = false>
; __device__ __forceinline__ void gemm_phase(PG8_LAS unsigned char* lds, const Gemm g, const Sched& S, const Epi& E, int wv) {
;     ...
;     for (;;) {
;         const bool has_next = S.next(ui + 1, nxt);
;         const char* nA = has_next ? (const char*)(nxt.sw ? g.A2 : g.A) + (size_t)nxt.pm * tstepA : cA; const char* nB = has_next ? (const char*)(nxt.sw ? g.Bt2 : g.Bt) + (size_t)nxt.pn * tstepB : cB;
;         for (int t = 0; t < nt; t += 2) {
;             const bool last = (t == nt - 2);
;             const char* a1 = cA + (size_t)(t + 1) * kstep;
;             const char* a2 = last ? nA : cA + (size_t)(t + 2) * kstep; const char* b2 = last ? nB : cB + (size_t)(t + 2) * kstep;
;             const char* a3 = a2 + kstep; const char* b3 = b2 + kstep;
;     ...
; #pragma unroll
;         for (int a = 0; a < 2; ++a)
; #pragma unroll
;             for (int b = 0; b < 2; ++b)
; #pragma unroll
;                 for (int m = 0; m < 4; ++m)
; #pragma unroll
;                     for (int n = 0; n < 2; ++n) acc[a][b][m][n] = (f32x4){0.f, 0.f, 0.f, 0.f};
.LBB0_1151:
	s_ashr_i32 s11, s10, 31
	s_lshl_b64 s[12:13], s[10:11], 20
	s_add_u32 s12, s30, s12
	s_addc_u32 s13, s31, s13
	s_and_b64 s[14:15], s[44:45], exec
	s_cselect_b32 s11, s13, s25
	s_cselect_b32 s19, s12, s24
	s_ashr_i32 s9, s8, 31
	s_lshl_b64 s[14:15], s[8:9], 20
	s_add_u32 s14, s0, s14
	s_addc_u32 s15, s1, s15
	s_and_b64 s[26:27], s[44:45], exec
	s_cselect_b32 s9, s15, s23
	s_cselect_b32 s21, s14, s22
	s_add_u32 s53, s22, 0x100
	s_addc_u32 s54, s23, 0
	s_add_u32 s22, s24, 0x80080
	s_waitcnt lgkmcnt(0)
	v_mov_b32_e32 v2, 0
	s_addc_u32 s23, s25, 0
	s_mov_b32 s55, -2
	v_mov_b32_e32 v3, v2
	v_mov_b32_e32 v4, v2
	v_mov_b32_e32 v5, v2
	v_mov_b32_e32 v6, v2
	v_mov_b32_e32 v7, v2
	v_mov_b32_e32 v8, v2
	v_mov_b32_e32 v9, v2
	v_mov_b32_e32 v18, v2
	v_mov_b32_e32 v19, v2
	v_mov_b32_e32 v20, v2
	v_mov_b32_e32 v21, v2
	v_mov_b32_e32 v22, v2
	v_mov_b32_e32 v23, v2
	v_mov_b32_e32 v24, v2
	v_mov_b32_e32 v25, v2
	v_mov_b32_e32 v34, v2
	v_mov_b32_e32 v35, v2
	v_mov_b32_e32 v36, v2
	v_mov_b32_e32 v37, v2
	v_mov_b32_e32 v38, v2
	v_mov_b32_e32 v39, v2
	v_mov_b32_e32 v40, v2
	v_mov_b32_e32 v41, v2
	v_mov_b32_e32 v50, v2
	v_mov_b32_e32 v51, v2
	v_mov_b32_e32 v52, v2
	v_mov_b32_e32 v53, v2
	v_mov_b32_e32 v54, v2
	v_mov_b32_e32 v55, v2
	v_mov_b32_e32 v56, v2
	v_mov_b32_e32 v57, v2
	v_mov_b32_e32 v10, v2
	v_mov_b32_e32 v11, v2
	v_mov_b32_e32 v12, v2
	v_mov_b32_e32 v13, v2
	v_mov_b32_e32 v14, v2
	v_mov_b32_e32 v15, v2
	v_mov_b32_e32 v16, v2
	v_mov_b32_e32 v17, v2
	v_mov_b32_e32 v26, v2
	v_mov_b32_e32 v27, v2
	v_mov_b32_e32 v28, v2
	v_mov_b32_e32 v29, v2
	v_mov_b32_e32 v30, v2
	v_mov_b32_e32 v31, v2
	v_mov_b32_e32 v32, v2
	v_mov_b32_e32 v33, v2
	v_mov_b32_e32 v42, v2
	v_mov_b32_e32 v43, v2
	v_mov_b32_e32 v44, v2
	v_mov_b32_e32 v45, v2
	v_mov_b32_e32 v46, v2
	v_mov_b32_e32 v47, v2
	v_mov_b32_e32 v48, v2
	v_mov_b32_e32 v49, v2
	v_mov_b32_e32 v58, v2
	v_mov_b32_e32 v59, v2
	v_mov_b32_e32 v60, v2
	v_mov_b32_e32 v61, v2
	v_mov_b32_e32 v62, v2
	v_mov_b32_e32 v63, v2
	v_mov_b32_e32 v64, v2
	v_mov_b32_e32 v65, v2
	v_mov_b32_e32 v66, v2
	v_mov_b32_e32 v67, v2
	v_mov_b32_e32 v68, v2
	v_mov_b32_e32 v69, v2
	v_mov_b32_e32 v70, v2
	v_mov_b32_e32 v71, v2
	v_mov_b32_e32 v72, v2
	v_mov_b32_e32 v73, v2
	v_mov_b32_e32 v82, v2
	v_mov_b32_e32 v83, v2
	v_mov_b32_e32 v84, v2
	v_mov_b32_e32 v85, v2
	v_mov_b32_e32 v86, v2
	v_mov_b32_e32 v87, v2
	v_mov_b32_e32 v88, v2
	v_mov_b32_e32 v89, v2
	v_mov_b32_e32 v98, v2
	v_mov_b32_e32 v99, v2
	v_mov_b32_e32 v100, v2
	v_mov_b32_e32 v101, v2
	v_mov_b32_e32 v102, v2
	v_mov_b32_e32 v103, v2
	v_mov_b32_e32 v104, v2
	v_mov_b32_e32 v105, v2
	v_mov_b32_e32 v114, v2
	v_mov_b32_e32 v115, v2
	v_mov_b32_e32 v116, v2
	v_mov_b32_e32 v117, v2
	v_mov_b32_e32 v118, v2
	v_mov_b32_e32 v119, v2
	v_mov_b32_e32 v120, v2
	v_mov_b32_e32 v121, v2
	v_mov_b32_e32 v74, v2
	v_mov_b32_e32 v75, v2
	v_mov_b32_e32 v76, v2
	v_mov_b32_e32 v77, v2
	v_mov_b32_e32 v78, v2
	v_mov_b32_e32 v79, v2
	v_mov_b32_e32 v80, v2
	v_mov_b32_e32 v81, v2
	v_mov_b32_e32 v90, v2
	v_mov_b32_e32 v91, v2
	v_mov_b32_e32 v92, v2
	v_mov_b32_e32 v93, v2
	v_mov_b32_e32 v94, v2
	v_mov_b32_e32 v95, v2
	v_mov_b32_e32 v96, v2
	v_mov_b32_e32 v97, v2
	v_mov_b32_e32 v106, v2
	v_mov_b32_e32 v107, v2
	v_mov_b32_e32 v108, v2
	v_mov_b32_e32 v109, v2
	v_mov_b32_e32 v110, v2
	v_mov_b32_e32 v111, v2
	v_mov_b32_e32 v112, v2
	v_mov_b32_e32 v113, v2
	v_mov_b32_e32 v122, v2
	v_mov_b32_e32 v123, v2
	v_mov_b32_e32 v124, v2
	v_mov_b32_e32 v125, v2
	v_mov_b32_e32 v126, v2
	v_mov_b32_e32 v127, v2
	v_mov_b32_e32 v128, v2
	v_mov_b32_e32 v129, v2
	.p2align 6

;     DI bool next(int i, pg8::Unit& o) const { if (i == 0 && has) { o = u; return true; } return false; }
; template <class Epi, class Sched, bool ALIGN_EPI = false, bool SP2 = false>
; __device__ __forceinline__ void gemm_phase(PG8_LAS unsigned char* lds, const Gemm g, const Sched& S, const Epi& E, int wv) {
;     ...
;     for (;;) {
;         const bool has_next = S.next(ui + 1, nxt);
;         const char* nA = has_next ? (const char*)(nxt.sw ? g.A2 : g.A) + (size_t)nxt.pm * tstepA : cA; const char* nB = has_next ? (const char*)(nxt.sw ? g.Bt2 : g.Bt) + (size_t)nxt.pn * tstepB : cB;
;         for (int t = 0; t < nt; t += 2) {
;             const bool last = (t == nt - 2);
;             const char* a1 = cA + (size_t)(t + 1) * kstep;
;             const char* a2 = last ? nA : cA + (size_t)(t + 2) * kstep; const char* b2 = last ? nB : cB + (size_t)(t + 2) * kstep;
;             const char* a3 = a2 + kstep; const char* b3 = b2 + kstep;
;     ...
; #pragma unroll
;         for (int a = 0; a < 2; ++a)
; #pragma unroll
;             for (int b = 0; b < 2; ++b)
; #pragma unroll
;                 for (int m = 0; m < 4; ++m)
; #pragma unroll
;                     for (int n = 0; n < 2; ++n) acc[a][b][m][n] = (f32x4){0.f, 0.f, 0.f, 0.f};
.LBB0_1239:
	s_ashr_i32 s11, s10, 31
	s_lshl_b64 s[12:13], s[10:11], 20
	s_add_u32 s12, s28, s12
	s_addc_u32 s13, s29, s13
	s_and_b64 s[14:15], s[40:41], exec
	s_cselect_b32 s11, s13, s23
	s_cselect_b32 s46, s12, s22
	s_ashr_i32 s9, s8, 31
	s_lshl_b64 s[14:15], s[8:9], 20
	s_add_u32 s14, s0, s14
	s_addc_u32 s15, s1, s15
	s_and_b64 s[24:25], s[40:41], exec
	s_cselect_b32 s9, s15, s21
	s_cselect_b32 s47, s14, s20
	s_add_u32 s48, s20, 0x100
	s_addc_u32 s49, s21, 0
	s_add_u32 s20, s22, 0x80080
	v_mov_b32_e32 v2, 0
	s_addc_u32 s21, s23, 0
	s_mov_b32 s50, -2
	v_mov_b32_e32 v3, v2
	v_mov_b32_e32 v4, v2
	v_mov_b32_e32 v5, v2
	v_mov_b32_e32 v6, v2
	v_mov_b32_e32 v7, v2
	v_mov_b32_e32 v8, v2
	v_mov_b32_e32 v9, v2
	v_mov_b32_e32 v18, v2
	v_mov_b32_e32 v19, v2
	v_mov_b32_e32 v20, v2
	v_mov_b32_e32 v21, v2
	v_mov_b32_e32 v22, v2
	v_mov_b32_e32 v23, v2
	v_mov_b32_e32 v24, v2
	v_mov_b32_e32 v25, v2
	v_mov_b32_e32 v34, v2
	v_mov_b32_e32 v35, v2
	v_mov_b32_e32 v36, v2
	v_mov_b32_e32 v37, v2
	v_mov_b32_e32 v38, v2
	v_mov_b32_e32 v39, v2
	v_mov_b32_e32 v40, v2
	v_mov_b32_e32 v41, v2
	v_mov_b32_e32 v50, v2
	v_mov_b32_e32 v51, v2
	v_mov_b32_e32 v52, v2
	v_mov_b32_e32 v53, v2
	v_mov_b32_e32 v54, v2
	v_mov_b32_e32 v55, v2
	v_mov_b32_e32 v56, v2
	v_mov_b32_e32 v57, v2
	v_mov_b32_e32 v10, v2
	v_mov_b32_e32 v11, v2
	v_mov_b32_e32 v12, v2
	v_mov_b32_e32 v13, v2
	v_mov_b32_e32 v14, v2
	v_mov_b32_e32 v15, v2
	v_mov_b32_e32 v16, v2
	v_mov_b32_e32 v17, v2
	v_mov_b32_e32 v26, v2
	v_mov_b32_e32 v27, v2
	v_mov_b32_e32 v28, v2
	v_mov_b32_e32 v29, v2
	v_mov_b32_e32 v30, v2
	v_mov_b32_e32 v31, v2
	v_mov_b32_e32 v32, v2
	v_mov_b32_e32 v33, v2
	v_mov_b32_e32 v42, v2
	v_mov_b32_e32 v43, v2
	v_mov_b32_e32 v44, v2
	v_mov_b32_e32 v45, v2
	v_mov_b32_e32 v46, v2
	v_mov_b32_e32 v47, v2
	v_mov_b32_e32 v48, v2
	v_mov_b32_e32 v49, v2
	v_mov_b32_e32 v58, v2
	v_mov_b32_e32 v59, v2
	v_mov_b32_e32 v60, v2
	v_mov_b32_e32 v61, v2
	v_mov_b32_e32 v62, v2
	v_mov_b32_e32 v63, v2
	v_mov_b32_e32 v64, v2
	v_mov_b32_e32 v65, v2
	v_mov_b32_e32 v66, v2
	v_mov_b32_e32 v67, v2
	v_mov_b32_e32 v68, v2
	v_mov_b32_e32 v69, v2
	v_mov_b32_e32 v70, v2
	v_mov_b32_e32 v71, v2
	v_mov_b32_e32 v72, v2
	v_mov_b32_e32 v73, v2
	v_mov_b32_e32 v82, v2
	v_mov_b32_e32 v83, v2
	v_mov_b32_e32 v84, v2
	v_mov_b32_e32 v85, v2
	v_mov_b32_e32 v86, v2
	v_mov_b32_e32 v87, v2
	v_mov_b32_e32 v88, v2
	v_mov_b32_e32 v89, v2
	v_mov_b32_e32 v98, v2
	v_mov_b32_e32 v99, v2
	v_mov_b32_e32 v100, v2
	v_mov_b32_e32 v101, v2
	v_mov_b32_e32 v102, v2
	v_mov_b32_e32 v103, v2
	v_mov_b32_e32 v104, v2
	v_mov_b32_e32 v105, v2
	v_mov_b32_e32 v114, v2
	v_mov_b32_e32 v115, v2
	v_mov_b32_e32 v116, v2
	v_mov_b32_e32 v117, v2
	v_mov_b32_e32 v118, v2
	v_mov_b32_e32 v119, v2
	v_mov_b32_e32 v120, v2
	v_mov_b32_e32 v121, v2
	v_mov_b32_e32 v74, v2
	v_mov_b32_e32 v75, v2
	v_mov_b32_e32 v76, v2
	v_mov_b32_e32 v77, v2
	v_mov_b32_e32 v78, v2
	v_mov_b32_e32 v79, v2
	v_mov_b32_e32 v80, v2
	v_mov_b32_e32 v81, v2
	v_mov_b32_e32 v90, v2
	v_mov_b32_e32 v91, v2
	v_mov_b32_e32 v92, v2
	v_mov_b32_e32 v93, v2
	v_mov_b32_e32 v94, v2
	v_mov_b32_e32 v95, v2
	v_mov_b32_e32 v96, v2
	v_mov_b32_e32 v97, v2
	v_mov_b32_e32 v106, v2
	v_mov_b32_e32 v107, v2
	v_mov_b32_e32 v108, v2
	v_mov_b32_e32 v109, v2
	v_mov_b32_e32 v110, v2
	v_mov_b32_e32 v111, v2
	v_mov_b32_e32 v112, v2
	v_mov_b32_e32 v113, v2
	v_mov_b32_e32 v122, v2
	v_mov_b32_e32 v123, v2
	v_mov_b32_e32 v124, v2
	v_mov_b32_e32 v125, v2
	v_mov_b32_e32 v126, v2
	v_mov_b32_e32 v127, v2
	v_mov_b32_e32 v128, v2
	v_mov_b32_e32 v129, v2
	.p2align 6

; template <class Epi, class Sched, bool ALIGN_EPI = false, bool SP2 = false>
; __device__ __forceinline__ void gemm_phase(PG8_LAS unsigned char* lds, const Gemm g, const Sched& S, const Epi& E, int wv) {
;     ...
;         for (int t = 0; t < nt; t += 2) {
;             const bool last = (t == nt - 2);
;             const char* a1 = cA + (size_t)(t + 1) * kstep;
;             const char* a2 = last ? nA : cA + (size_t)(t + 2) * kstep; const char* b2 = last ? nB : cB + (size_t)(t + 2) * kstep;
;             const char* a3 = a2 + kstep; const char* b3 = b2 + kstep;
;     ...
; #pragma unroll
;         for (int a = 0; a < 2; ++a)
; #pragma unroll
;             for (int b = 0; b < 2; ++b)
; #pragma unroll
;                 for (int m = 0; m < 4; ++m)
; #pragma unroll
;                     for (int n = 0; n < 2; ++n) acc[a][b][m][n] = (f32x4){0.f, 0.f, 0.f, 0.f};
.LBB0_1323:
	s_add_u32 s48, s18, 0x100
	v_mov_b32_e32 v2, 0
	s_addc_u32 s49, s19, 0
	s_mov_b32 s50, -2
	s_waitcnt lgkmcnt(0)
	v_mov_b32_e32 v3, v2
	v_mov_b32_e32 v4, v2
	v_mov_b32_e32 v5, v2
	v_mov_b32_e32 v6, v2
	v_mov_b32_e32 v7, v2
	v_mov_b32_e32 v8, v2
	v_mov_b32_e32 v9, v2
	v_mov_b32_e32 v18, v2
	v_mov_b32_e32 v19, v2
	v_mov_b32_e32 v20, v2
	v_mov_b32_e32 v21, v2
	v_mov_b32_e32 v22, v2
	v_mov_b32_e32 v23, v2
	v_mov_b32_e32 v24, v2
	v_mov_b32_e32 v25, v2
	v_mov_b32_e32 v34, v2
	v_mov_b32_e32 v35, v2
	v_mov_b32_e32 v36, v2
	v_mov_b32_e32 v37, v2
	v_mov_b32_e32 v38, v2
	v_mov_b32_e32 v39, v2
	v_mov_b32_e32 v40, v2
	v_mov_b32_e32 v41, v2
	v_mov_b32_e32 v50, v2
	v_mov_b32_e32 v51, v2
	v_mov_b32_e32 v52, v2
	v_mov_b32_e32 v53, v2
	v_mov_b32_e32 v54, v2
	v_mov_b32_e32 v55, v2
	v_mov_b32_e32 v56, v2
	v_mov_b32_e32 v57, v2
	v_mov_b32_e32 v10, v2
	v_mov_b32_e32 v11, v2
	v_mov_b32_e32 v12, v2
	v_mov_b32_e32 v13, v2
	v_mov_b32_e32 v14, v2
	v_mov_b32_e32 v15, v2
	v_mov_b32_e32 v16, v2
	v_mov_b32_e32 v17, v2
	v_mov_b32_e32 v26, v2
	v_mov_b32_e32 v27, v2
	v_mov_b32_e32 v28, v2
	v_mov_b32_e32 v29, v2
	v_mov_b32_e32 v30, v2
	v_mov_b32_e32 v31, v2
	v_mov_b32_e32 v32, v2
	v_mov_b32_e32 v33, v2
	v_mov_b32_e32 v42, v2
	v_mov_b32_e32 v43, v2
	v_mov_b32_e32 v44, v2
	v_mov_b32_e32 v45, v2
	v_mov_b32_e32 v46, v2
	v_mov_b32_e32 v47, v2
	v_mov_b32_e32 v48, v2
	v_mov_b32_e32 v49, v2
	v_mov_b32_e32 v58, v2
	v_mov_b32_e32 v59, v2
	v_mov_b32_e32 v60, v2
	v_mov_b32_e32 v61, v2
	v_mov_b32_e32 v62, v2
	v_mov_b32_e32 v63, v2
	v_mov_b32_e32 v64, v2
	v_mov_b32_e32 v65, v2
	v_mov_b32_e32 v66, v2
	v_mov_b32_e32 v67, v2
	v_mov_b32_e32 v68, v2
	v_mov_b32_e32 v69, v2
	v_mov_b32_e32 v70, v2
	v_mov_b32_e32 v71, v2
	v_mov_b32_e32 v72, v2
	v_mov_b32_e32 v73, v2
	v_mov_b32_e32 v82, v2
	v_mov_b32_e32 v83, v2
	v_mov_b32_e32 v84, v2
	v_mov_b32_e32 v85, v2
	v_mov_b32_e32 v86, v2
	v_mov_b32_e32 v87, v2
	v_mov_b32_e32 v88, v2
	v_mov_b32_e32 v89, v2
	v_mov_b32_e32 v98, v2
	v_mov_b32_e32 v99, v2
	v_mov_b32_e32 v100, v2
	v_mov_b32_e32 v101, v2
	v_mov_b32_e32 v102, v2
	v_mov_b32_e32 v103, v2
	v_mov_b32_e32 v104, v2
	v_mov_b32_e32 v105, v2
	v_mov_b32_e32 v114, v2
	v_mov_b32_e32 v115, v2
	v_mov_b32_e32 v116, v2
	v_mov_b32_e32 v117, v2
	v_mov_b32_e32 v118, v2
	v_mov_b32_e32 v119, v2
	v_mov_b32_e32 v120, v2
	v_mov_b32_e32 v121, v2
	v_mov_b32_e32 v74, v2
	v_mov_b32_e32 v75, v2
	v_mov_b32_e32 v76, v2
	v_mov_b32_e32 v77, v2
	v_mov_b32_e32 v78, v2
	v_mov_b32_e32 v79, v2
	v_mov_b32_e32 v80, v2
	v_mov_b32_e32 v81, v2
	v_mov_b32_e32 v90, v2
	v_mov_b32_e32 v91, v2
	v_mov_b32_e32 v92, v2
	v_mov_b32_e32 v93, v2
	v_mov_b32_e32 v94, v2
	v_mov_b32_e32 v95, v2
	v_mov_b32_e32 v96, v2
	v_mov_b32_e32 v97, v2
	v_mov_b32_e32 v106, v2
	v_mov_b32_e32 v107, v2
	v_mov_b32_e32 v108, v2
	v_mov_b32_e32 v109, v2
	v_mov_b32_e32 v110, v2
	v_mov_b32_e32 v111, v2
	v_mov_b32_e32 v112, v2
	v_mov_b32_e32 v113, v2
	v_mov_b32_e32 v122, v2
	v_mov_b32_e32 v123, v2
	v_mov_b32_e32 v124, v2
	v_mov_b32_e32 v125, v2
	v_mov_b32_e32 v126, v2
	v_mov_b32_e32 v127, v2
	v_mov_b32_e32 v128, v2
	v_mov_b32_e32 v129, v2
	.p2align 6
